# attention first->second half: barrier moved in front of the last PV group, next QK^T's first K-fragment reads issued between that group's MFMAs
# baseline (speedup 1.0000x reference)
.LBB0_433:
	ds_read_b128 v[64:67], v166 offset:49152
	ds_read_b128 v[68:71], v166 offset:57344
	ds_read_b128 v[176:179], v167 offset:49152
	ds_read_b128 v[198:201], v167 offset:57344
	ds_read_b128 v[202:205], v168 offset:49152
	ds_read_b128 v[210:213], v168 offset:57344
	s_add_u32 m0, s86, 0x8000
	s_nop 0
	global_load_lds_dwordx4 v247, s[82:83]
	s_add_u32 m0, s86, 0x8400
	s_nop 0
	global_load_lds_dwordx4 v248, s[82:83]
	s_add_u32 s82, s82, 0x8000
	s_addc_u32 s83, s83, 0
	v_exp_f32_e32 v142, v142
	v_exp_f32_e32 v143, v143
	v_exp_f32_e32 v180, v140
	v_exp_f32_e32 v181, v141
	v_exp_f32_e32 v206, v138
	v_exp_f32_e32 v207, v135
	v_exp_f32_e32 v148, v148
	v_exp_f32_e32 v149, v149
	v_exp_f32_e32 v209, v146
	s_waitcnt lgkmcnt(5)
	v_mfma_f32_32x32x16_bf16 v[80:95], v[64:67], v[124:127], 0
	s_waitcnt lgkmcnt(4)
	v_mfma_f32_32x32x16_bf16 v[64:79], v[68:71], v[124:127], 0
	v_cvt_pk_bf16_f32 v135, v192, v193
	v_cvt_pk_bf16_f32 v138, v182, v183
	v_cvt_pk_bf16_f32 v140, v185, v187
	v_cvt_pk_bf16_f32 v141, v188, v189
	s_nop 0
	s_waitcnt lgkmcnt(3)
	v_mfma_f32_32x32x16_bf16 v[80:95], v[176:179], v[120:123], v[80:95]
	ds_read_b128 v[176:179], v169 offset:49152
	ds_read_b128 v[214:217], v169 offset:57344
	ds_read_b128 v[218:221], v170 offset:49152
	ds_read_b128 v[222:225], v170 offset:57344
	ds_read_b128 v[226:229], v171 offset:49152
	ds_read_b128 v[230:233], v171 offset:57344
	ds_read_b128 v[234:237], v172 offset:49152
	ds_read_b128 v[238:241], v172 offset:57344
	s_waitcnt lgkmcnt(10)
	v_mfma_f32_32x32x16_bf16 v[64:79], v[198:201], v[120:123], v[64:79]
	ds_read_b128 v[198:201], v173 offset:49152
	ds_read_b128 v[242:245], v173 offset:57344
	s_waitcnt lgkmcnt(11)
	v_mfma_f32_32x32x16_bf16 v[80:95], v[202:205], v[112:115], v[80:95]
	v_exp_f32_e32 v205, v134
	v_add_f32_e32 v134, v191, v190
	v_add_f32_e32 v134, v192, v134
	v_add_f32_e32 v134, v193, v134
	v_add_f32_e32 v134, v194, v134
	v_add_f32_e32 v134, v196, v134
	s_waitcnt lgkmcnt(10)
	v_mfma_f32_32x32x16_bf16 v[64:79], v[210:213], v[112:115], v[64:79]
	v_add_f32_e32 v134, v195, v134
	v_add_f32_e32 v134, v197, v134
	v_add_f32_e32 v134, v182, v134
	v_add_f32_e32 v134, v183, v134
	v_add_f32_e32 v134, v184, v134
	v_add_f32_e32 v134, v186, v134
	v_add_f32_e32 v134, v185, v134
	s_waitcnt lgkmcnt(9)
	v_mfma_f32_32x32x16_bf16 v[80:95], v[176:179], v[116:119], v[80:95]
	v_add_f32_e32 v134, v187, v134
	v_add_f32_e32 v134, v188, v134
	v_add_f32_e32 v134, v189, v134
	v_add_f32_e32 v134, v142, v134
	v_exp_f32_e32 v202, v139
	v_add_f32_e32 v134, v143, v134
	v_exp_f32_e32 v203, v136
	s_waitcnt lgkmcnt(8)
	v_mfma_f32_32x32x16_bf16 v[64:79], v[214:217], v[116:119], v[64:79]
	v_add_f32_e32 v134, v180, v134
	v_exp_f32_e32 v204, v137
	v_add_f32_e32 v134, v181, v134
	v_add_f32_e32 v134, v206, v134
	v_add_f32_e32 v134, v202, v134
	v_add_f32_e32 v134, v203, v134
	v_add_f32_e32 v134, v204, v134
	s_waitcnt lgkmcnt(7)
	v_mfma_f32_32x32x16_bf16 v[80:95], v[218:221], v[108:111], v[80:95]
	v_add_f32_e32 v134, v205, v134
	v_exp_f32_e32 v210, v147
	v_add_f32_e32 v134, v207, v134
	v_exp_f32_e32 v211, v144
	v_add_f32_e32 v134, v148, v134
	v_exp_f32_e32 v212, v145
	v_add_f32_e32 v134, v149, v134
	s_waitcnt lgkmcnt(6)
	v_mfma_f32_32x32x16_bf16 v[64:79], v[222:225], v[108:111], v[64:79]
	v_add_f32_e32 v134, v209, v134
	v_add_f32_e32 v134, v210, v134
	v_add_f32_e32 v134, v211, v134
	v_add_f32_e32 v176, v212, v134
	v_cvt_pk_bf16_f32 v134, v190, v191
	v_cvt_pk_bf16_f32 v136, v194, v196
	s_waitcnt lgkmcnt(5)
	v_mfma_f32_32x32x16_bf16 v[80:95], v[226:229], v[104:107], v[80:95]
	v_cvt_pk_bf16_f32 v137, v195, v197
	v_cvt_pk_bf16_f32 v139, v184, v186
	v_cvt_pk_bf16_f32 v142, v142, v143
	s_waitcnt lgkmcnt(4)
	v_mfma_f32_32x32x16_bf16 v[64:79], v[230:233], v[104:107], v[64:79]
	ds_read_b64_tr_b16 v[218:219], v161 offset:0
	ds_read_b64_tr_b16 v[220:221], v161 offset:2048
	ds_read_b64_tr_b16 v[222:223], v161 offset:4096
	ds_read_b64_tr_b16 v[224:225], v161 offset:6144
	ds_read_b64_tr_b16 v[226:227], v161 offset:8192
	ds_read_b64_tr_b16 v[228:229], v161 offset:10240
	ds_read_b64_tr_b16 v[230:231], v161 offset:12288
	ds_read_b64_tr_b16 v[232:233], v161 offset:14336
	v_cvt_pk_bf16_f32 v143, v180, v181
	v_cvt_pk_bf16_f32 v144, v206, v202
	v_cvt_pk_bf16_f32 v145, v203, v204
	v_cvt_pk_bf16_f32 v146, v205, v207
	v_cvt_pk_bf16_f32 v147, v148, v149
	v_cvt_pk_bf16_f32 v148, v209, v210
	v_cvt_pk_bf16_f32 v149, v211, v212
	s_waitcnt lgkmcnt(11)
	v_mfma_f32_32x32x16_bf16 v[80:95], v[234:237], v[100:103], v[80:95]
	s_waitcnt lgkmcnt(10)
	v_mfma_f32_32x32x16_bf16 v[64:79], v[238:241], v[100:103], v[64:79]
	s_waitcnt lgkmcnt(9)
	v_mfma_f32_32x32x16_bf16 v[80:95], v[198:201], v[96:99], v[80:95]
	s_waitcnt lgkmcnt(8)
	v_mfma_f32_32x32x16_bf16 v[64:79], v[242:245], v[96:99], v[64:79]
	s_waitcnt lgkmcnt(0)
	s_nop 0
	v_mfma_f32_32x32x16_bf16 v[0:15], v[134:137], v[218:221], v[0:15]
	ds_read_b64_tr_b16 v[196:197], v161 offset:0x200
	ds_read_b64_tr_b16 v[198:199], v161 offset:0xa00
	v_max_f32_e32 v234, v80, v81
	v_max3_f32 v234, v234, v82, v83
	v_max3_f32 v234, v234, v84, v85
	v_max3_f32 v234, v234, v86, v87
	v_max3_f32 v234, v234, v88, v89
	v_mfma_f32_32x32x16_bf16 v[0:15], v[138:141], v[222:225], v[0:15]
	ds_read_b64_tr_b16 v[200:201], v161 offset:0x1200
	ds_read_b64_tr_b16 v[202:203], v161 offset:0x1a00
	v_max3_f32 v234, v234, v90, v91
	v_max3_f32 v234, v234, v92, v93
	v_max3_f32 v234, v234, v94, v95
	v_max3_f32 v234, v234, v64, v65
	v_max3_f32 v234, v234, v66, v67
	v_mfma_f32_32x32x16_bf16 v[0:15], v[142:145], v[226:229], v[0:15]
	ds_read_b64_tr_b16 v[204:205], v161 offset:0x2200
	ds_read_b64_tr_b16 v[206:207], v161 offset:0x2a00
	ds_read_b64_tr_b16 v[214:215], v161 offset:0x3200
	ds_read_b64_tr_b16 v[216:217], v161 offset:0x3a00
	v_max3_f32 v234, v234, v68, v69
	v_max3_f32 v234, v234, v70, v71
	v_max3_f32 v234, v234, v72, v73
	v_max3_f32 v234, v234, v74, v75
	v_max3_f32 v234, v234, v76, v77
	s_waitcnt lgkmcnt(0)
	v_mfma_f32_32x32x16_bf16 v[0:15], v[146:149], v[230:233], v[0:15]
	v_max3_f32 v234, v234, v78, v79
	v_mov_b32_e32 v235, v234
	v_mfma_f32_32x32x16_bf16 v[48:63], v[134:137], v[196:199], v[48:63]
	ds_read_b64_tr_b16 v[196:197], v161 offset:0x400
	ds_read_b64_tr_b16 v[198:199], v161 offset:0xc00
	v_permlane32_swap_b32_e32 v234, v235
	v_max_f32_e32 v234, v234, v235
	v_mfma_f32_32x32x16_bf16 v[48:63], v[138:141], v[200:203], v[48:63]
	ds_read_b64_tr_b16 v[200:201], v161 offset:0x1400
	ds_read_b64_tr_b16 v[202:203], v161 offset:0x1c00
	v_sub_f32_e32 v235, v234, v175
	v_max_f32_e32 v234, v175, v234
	v_sub_f32_e32 v236, v175, v234
	v_mul_f32_e32 v236, 0x3e0293ee, v236
	v_mfma_f32_32x32x16_bf16 v[48:63], v[142:145], v[204:207], v[48:63]
	ds_read_b64_tr_b16 v[204:205], v161 offset:0x2400
	ds_read_b64_tr_b16 v[206:207], v161 offset:0x2c00
	ds_read_b64_tr_b16 v[210:211], v161 offset:0x3400
	ds_read_b64_tr_b16 v[212:213], v161 offset:0x3c00
	v_exp_f32_e32 v236, v236
	v_cmp_ge_f32_e32 vcc, s15, v235
	s_cmp_eq_u64 vcc, exec
	s_cselect_b64 s[8:9], -1, 0
	s_waitcnt lgkmcnt(0)
	v_mfma_f32_32x32x16_bf16 v[48:63], v[146:149], v[214:217], v[48:63]
	v_cndmask_b32_e64 v179, v236, 1.0, s[8:9]
	v_cndmask_b32_e64 v234, v234, v175, s[8:9]
	v_mul_f32_e32 v238, 0xbe0293ee, v234
	v_fmamk_f32 v88, v88, 0x3e0293ee, v238
	v_fmamk_f32 v89, v89, 0x3e0293ee, v238
	v_fmamk_f32 v80, v80, 0x3e0293ee, v238
	v_fmamk_f32 v81, v81, 0x3e0293ee, v238
	v_mfma_f32_32x32x16_bf16 v[32:47], v[134:137], v[196:199], v[32:47]
	ds_read_b64_tr_b16 v[196:197], v161 offset:0x600
	ds_read_b64_tr_b16 v[198:199], v161 offset:0xe00
	v_fmamk_f32 v82, v82, 0x3e0293ee, v238
	v_fmamk_f32 v83, v83, 0x3e0293ee, v238
	v_fmamk_f32 v84, v84, 0x3e0293ee, v238
	v_fmamk_f32 v85, v85, 0x3e0293ee, v238
	v_fmamk_f32 v86, v86, 0x3e0293ee, v238
	v_fmamk_f32 v87, v87, 0x3e0293ee, v238
	v_fmamk_f32 v90, v90, 0x3e0293ee, v238
	v_fmamk_f32 v91, v91, 0x3e0293ee, v238
	v_mfma_f32_32x32x16_bf16 v[32:47], v[138:141], v[200:203], v[32:47]
	ds_read_b64_tr_b16 v[200:201], v161 offset:0x1600
	ds_read_b64_tr_b16 v[202:203], v161 offset:0x1e00
	v_fmamk_f32 v92, v92, 0x3e0293ee, v238
	v_fmamk_f32 v93, v93, 0x3e0293ee, v238
	v_fmamk_f32 v94, v94, 0x3e0293ee, v238
	v_fmamk_f32 v95, v95, 0x3e0293ee, v238
	v_fmamk_f32 v188, v64, 0x3e0293ee, v238
	v_fmamk_f32 v189, v65, 0x3e0293ee, v238
	v_fmamk_f32 v190, v66, 0x3e0293ee, v238
	v_fmamk_f32 v191, v67, 0x3e0293ee, v238
	v_mfma_f32_32x32x16_bf16 v[32:47], v[142:145], v[204:207], v[32:47]
	ds_read_b64_tr_b16 v[204:205], v161 offset:0x2600
	ds_read_b64_tr_b16 v[206:207], v161 offset:0x2e00
	ds_read_b64_tr_b16 v[214:215], v161 offset:0x3600
	ds_read_b64_tr_b16 v[216:217], v161 offset:0x3e00
	v_fmamk_f32 v182, v70, 0x3e0293ee, v238
	v_fmamk_f32 v183, v71, 0x3e0293ee, v238
	v_fmamk_f32 v184, v72, 0x3e0293ee, v238
	v_fmamk_f32 v185, v73, 0x3e0293ee, v238
	v_fmamk_f32 v186, v74, 0x3e0293ee, v238
	v_fmamk_f32 v187, v75, 0x3e0293ee, v238
	s_waitcnt lgkmcnt(0)
	v_mfma_f32_32x32x16_bf16 v[32:47], v[146:149], v[210:213], v[32:47]
	v_fmamk_f32 v192, v68, 0x3e0293ee, v238
	v_fmamk_f32 v181, v69, 0x3e0293ee, v238
	v_fmamk_f32 v180, v76, 0x3e0293ee, v238
	s_waitcnt vmcnt(0)
	s_barrier
	s_add_u32 m0, s86, 0x0
	s_nop 0
	global_load_lds_dwordx4 v249, s[84:85]
	s_add_u32 m0, s86, 0x380
	s_nop 0
	global_load_lds_dwordx4 v249, s[84:85] offset:128
	s_add_u32 s84, s84, 0x8000
	s_addc_u32 s85, s85, 0
	s_add_u32 m0, s86, 0xc000
	s_nop 0
	global_load_lds_dwordx4 v247, s[82:83]
	s_add_u32 m0, s86, 0xc400
	s_nop 0
	global_load_lds_dwordx4 v248, s[82:83]
	s_add_u32 s82, s82, 0x8000
	s_addc_u32 s83, s83, 0
	v_mfma_f32_32x32x16_bf16 v[16:31], v[134:137], v[196:199], v[16:31]
	v_fmamk_f32 v193, v77, 0x3e0293ee, v238
	v_fmamk_f32 v194, v78, 0x3e0293ee, v238
	v_fmamk_f32 v177, v79, 0x3e0293ee, v238
	ds_read_b128 v[64:67], v166 offset:32768
	ds_read_b128 v[68:71], v166 offset:40960
	ds_read_b128 v[196:199], v167 offset:32768
	v_mov_b32_e32 v134, v234
	v_exp_f32_e32 v135, v88
	v_exp_f32_e32 v136, v89
	v_exp_f32_e32 v137, v90
	v_mfma_f32_32x32x16_bf16 v[16:31], v[138:141], v[200:203], v[16:31]
	ds_read_b128 v[200:203], v167 offset:40960
	v_exp_f32_e32 v139, v91
	v_exp_f32_e32 v138, v92
	v_exp_f32_e32 v140, v93
	v_exp_f32_e32 v141, v94
	v_mfma_f32_32x32x16_bf16 v[16:31], v[142:145], v[204:207], v[16:31]
	ds_read_b128 v[204:207], v168 offset:32768
	ds_read_b128 v[210:213], v168 offset:40960
	v_exp_f32_e32 v142, v95
	v_exp_f32_e32 v143, v80
	v_exp_f32_e32 v144, v81
	v_exp_f32_e32 v145, v82
	v_mfma_f32_32x32x16_bf16 v[16:31], v[146:149], v[214:217], v[16:31]
	v_exp_f32_e32 v146, v83
	v_exp_f32_e32 v147, v84
	v_exp_f32_e32 v149, v85
	v_exp_f32_e32 v148, v86
	v_exp_f32_e32 v175, v87
	v_cmp_gt_f32_e32 vcc, 1.0, v179
	s_nop 3
	s_cbranch_vccz .LBB0_437
	s_and_saveexec_b64 s[2:3], s[6:7]
	ds_write_b32 v158, v179 offset:128
	s_or_b64 exec, exec, s[2:3]
	s_waitcnt lgkmcnt(0)
	v_add_u32_e32 v234, v131, v128
	ds_read_b128 v[218:221], v234 offset:224
	ds_read_b128 v[222:225], v234 offset:192
	ds_read_b128 v[226:229], v234 offset:160
	ds_read_b128 v[230:233], v234 offset:128
	s_waitcnt lgkmcnt(3)
	v_pk_mul_f32 v[12:13], v[12:13], v[218:219]
	s_waitcnt lgkmcnt(2)
	v_pk_mul_f32 v[8:9], v[8:9], v[222:223]
	s_waitcnt lgkmcnt(1)
	v_pk_mul_f32 v[4:5], v[4:5], v[226:227]
	v_pk_mul_f32 v[14:15], v[14:15], v[220:221]
	v_pk_mul_f32 v[10:11], v[10:11], v[224:225]
	v_pk_mul_f32 v[6:7], v[6:7], v[228:229]
	s_waitcnt lgkmcnt(0)
	v_pk_mul_f32 v[2:3], v[2:3], v[232:233]
	v_pk_mul_f32 v[0:1], v[0:1], v[230:231]
	v_pk_mul_f32 v[60:61], v[60:61], v[218:219]
	v_pk_mul_f32 v[56:57], v[56:57], v[222:223]
	v_pk_mul_f32 v[52:53], v[52:53], v[226:227]
	v_pk_mul_f32 v[62:63], v[62:63], v[220:221]
	v_pk_mul_f32 v[58:59], v[58:59], v[224:225]
	v_pk_mul_f32 v[54:55], v[54:55], v[228:229]
	v_pk_mul_f32 v[50:51], v[50:51], v[232:233]
	v_pk_mul_f32 v[48:49], v[48:49], v[230:231]
	v_pk_mul_f32 v[44:45], v[44:45], v[218:219]
	v_pk_mul_f32 v[40:41], v[40:41], v[222:223]
	v_pk_mul_f32 v[36:37], v[36:37], v[226:227]
	v_pk_mul_f32 v[46:47], v[46:47], v[220:221]
	v_pk_mul_f32 v[42:43], v[42:43], v[224:225]
	v_pk_mul_f32 v[38:39], v[38:39], v[228:229]
	v_pk_mul_f32 v[34:35], v[34:35], v[232:233]
	v_pk_mul_f32 v[32:33], v[32:33], v[230:231]
	v_pk_mul_f32 v[28:29], v[28:29], v[218:219]
	v_pk_mul_f32 v[24:25], v[24:25], v[222:223]
	v_pk_mul_f32 v[20:21], v[20:21], v[226:227]
	v_pk_mul_f32 v[30:31], v[30:31], v[220:221]
	v_pk_mul_f32 v[26:27], v[26:27], v[224:225]
	v_pk_mul_f32 v[22:23], v[22:23], v[228:229]
	v_pk_mul_f32 v[18:19], v[18:19], v[232:233]
	v_pk_mul_f32 v[16:17], v[16:17], v[230:231]
.LBB0_437:
	v_exp_f32_e32 v188, v188
	v_exp_f32_e32 v189, v189
	v_exp_f32_e32 v190, v190
	v_exp_f32_e32 v191, v191
	v_exp_f32_e32 v192, v192
	v_exp_f32_e32 v195, v181
	v_exp_f32_e32 v182, v182
	v_exp_f32_e32 v183, v183
	v_exp_f32_e32 v184, v184
	s_waitcnt lgkmcnt(5)
	v_mfma_f32_32x32x16_bf16 v[80:95], v[64:67], v[124:127], 0
	s_waitcnt lgkmcnt(4)
	v_mfma_f32_32x32x16_bf16 v[64:79], v[68:71], v[124:127], 0
	v_exp_f32_e32 v185, v185
	v_exp_f32_e32 v186, v186
	v_exp_f32_e32 v187, v187
	v_exp_f32_e32 v193, v193
	v_exp_f32_e32 v194, v194
	v_exp_f32_e32 v177, v177
	s_waitcnt lgkmcnt(3)
	v_mfma_f32_32x32x16_bf16 v[80:95], v[196:199], v[120:123], v[80:95]
	ds_read_b128 v[196:199], v169 offset:32768
	ds_read_b128 v[214:217], v169 offset:40960
	ds_read_b128 v[218:221], v170 offset:32768
	ds_read_b128 v[222:225], v170 offset:40960
	ds_read_b128 v[226:229], v171 offset:32768
	ds_read_b128 v[230:233], v171 offset:40960
	ds_read_b128 v[234:237], v172 offset:32768
	ds_read_b128 v[238:241], v172 offset:40960
	s_waitcnt lgkmcnt(10)
	v_mfma_f32_32x32x16_bf16 v[64:79], v[200:203], v[120:123], v[64:79]
	ds_read_b128 v[200:203], v173 offset:32768
	ds_read_b128 v[242:245], v173 offset:40960
	s_waitcnt lgkmcnt(11)
	v_mfma_f32_32x32x16_bf16 v[80:95], v[204:207], v[112:115], v[80:95]
	v_exp_f32_e32 v204, v180
	v_add_f32_e32 v180, v144, v143
	v_add_f32_e32 v180, v145, v180
	v_add_f32_e32 v180, v146, v180
	v_add_f32_e32 v180, v147, v180
	v_add_f32_e32 v180, v149, v180
	s_waitcnt lgkmcnt(10)
	v_mfma_f32_32x32x16_bf16 v[64:79], v[210:213], v[112:115], v[64:79]
	v_add_f32_e32 v180, v148, v180
	v_add_f32_e32 v180, v175, v180
	v_add_f32_e32 v180, v135, v180
	v_add_f32_e32 v180, v136, v180
	v_add_f32_e32 v180, v137, v180
	v_add_f32_e32 v180, v139, v180
	v_add_f32_e32 v180, v138, v180
	s_waitcnt lgkmcnt(9)
	v_mfma_f32_32x32x16_bf16 v[80:95], v[196:199], v[116:119], v[80:95]
	v_add_f32_e32 v180, v140, v180
	v_add_f32_e32 v180, v141, v180
	v_add_f32_e32 v180, v142, v180
	v_add_f32_e32 v180, v188, v180
	v_add_f32_e32 v180, v189, v180
	v_add_f32_e32 v180, v190, v180
	v_add_f32_e32 v180, v191, v180
	s_waitcnt lgkmcnt(8)
	v_mfma_f32_32x32x16_bf16 v[64:79], v[214:217], v[116:119], v[64:79]
	v_add_f32_e32 v180, v192, v180
	v_add_f32_e32 v180, v195, v180
	v_add_f32_e32 v180, v182, v180
	v_add_f32_e32 v180, v183, v180
	v_add_f32_e32 v180, v184, v180
	v_add_f32_e32 v180, v185, v180
	v_add_f32_e32 v180, v186, v180
	s_waitcnt lgkmcnt(7)
	v_mfma_f32_32x32x16_bf16 v[80:95], v[218:221], v[108:111], v[80:95]
	v_add_f32_e32 v180, v187, v180
	v_add_f32_e32 v180, v204, v180
	v_add_f32_e32 v180, v193, v180
	v_add_f32_e32 v180, v194, v180
	v_add_f32_e32 v180, v177, v180
	s_waitcnt lgkmcnt(6)
	v_mfma_f32_32x32x16_bf16 v[64:79], v[222:225], v[108:111], v[64:79]
	v_cvt_pk_bf16_f32 v144, v143, v144
	v_cvt_pk_bf16_f32 v145, v145, v146
	v_cvt_pk_bf16_f32 v146, v147, v149
	v_cvt_pk_bf16_f32 v147, v148, v175
	v_cvt_pk_bf16_f32 v136, v135, v136
	v_cvt_pk_bf16_f32 v137, v137, v139
	v_cvt_pk_bf16_f32 v138, v138, v140
	s_waitcnt lgkmcnt(5)
	v_mfma_f32_32x32x16_bf16 v[80:95], v[226:229], v[104:107], v[80:95]
	v_cvt_pk_bf16_f32 v139, v141, v142
	v_cvt_pk_bf16_f32 v140, v188, v189
	v_cvt_pk_bf16_f32 v141, v190, v191
	v_cvt_pk_bf16_f32 v142, v192, v195
	v_cvt_pk_bf16_f32 v143, v182, v183
	v_cvt_pk_bf16_f32 v182, v184, v185
	v_cvt_pk_bf16_f32 v183, v186, v187
	s_waitcnt lgkmcnt(4)
	v_mfma_f32_32x32x16_bf16 v[64:79], v[230:233], v[104:107], v[64:79]
	ds_read_b64_tr_b16 v[218:219], v160 offset:0
	ds_read_b64_tr_b16 v[220:221], v160 offset:2048
	ds_read_b64_tr_b16 v[222:223], v160 offset:4096
	ds_read_b64_tr_b16 v[224:225], v160 offset:6144
	ds_read_b64_tr_b16 v[226:227], v160 offset:8192
	ds_read_b64_tr_b16 v[228:229], v160 offset:10240
	ds_read_b64_tr_b16 v[230:231], v160 offset:12288
	ds_read_b64_tr_b16 v[232:233], v160 offset:14336
	v_cvt_pk_bf16_f32 v184, v204, v193
	v_cvt_pk_bf16_f32 v185, v194, v177
	s_waitcnt lgkmcnt(11)
	v_mfma_f32_32x32x16_bf16 v[80:95], v[234:237], v[100:103], v[80:95]
	s_waitcnt lgkmcnt(10)
	v_mfma_f32_32x32x16_bf16 v[64:79], v[238:241], v[100:103], v[64:79]
	s_waitcnt lgkmcnt(9)
	v_mfma_f32_32x32x16_bf16 v[80:95], v[200:203], v[96:99], v[80:95]
	s_waitcnt lgkmcnt(8)
	v_mfma_f32_32x32x16_bf16 v[64:79], v[242:245], v[96:99], v[64:79]
	s_waitcnt lgkmcnt(0)
	s_nop 0
	v_mfma_f32_32x32x16_bf16 v[0:15], v[144:147], v[218:221], v[0:15]
	ds_read_b64_tr_b16 v[202:203], v160 offset:0x200
	ds_read_b64_tr_b16 v[204:205], v160 offset:0xa00
	v_max_f32_e32 v242, v80, v81
	v_max3_f32 v242, v242, v82, v83
	v_max3_f32 v242, v242, v84, v85
	v_max3_f32 v242, v242, v86, v87
	v_max3_f32 v242, v242, v88, v89
	v_mfma_f32_32x32x16_bf16 v[0:15], v[136:139], v[222:225], v[0:15]
	ds_read_b64_tr_b16 v[210:211], v160 offset:0x1200
	ds_read_b64_tr_b16 v[212:213], v160 offset:0x1a00
	v_max3_f32 v242, v242, v90, v91
	v_max3_f32 v242, v242, v92, v93
	v_max3_f32 v242, v242, v94, v95
	v_max3_f32 v242, v242, v64, v65
	v_max3_f32 v242, v242, v66, v67
	v_mfma_f32_32x32x16_bf16 v[0:15], v[140:143], v[226:229], v[0:15]
	ds_read_b64_tr_b16 v[214:215], v160 offset:0x2200
	ds_read_b64_tr_b16 v[216:217], v160 offset:0x2a00
	ds_read_b64_tr_b16 v[222:223], v160 offset:0x3200
	ds_read_b64_tr_b16 v[224:225], v160 offset:0x3a00
	v_max3_f32 v242, v242, v68, v69
	v_max3_f32 v242, v242, v70, v71
	v_max3_f32 v242, v242, v72, v73
	v_max3_f32 v242, v242, v74, v75
	v_max3_f32 v242, v242, v76, v77
	s_waitcnt lgkmcnt(0)
	v_mfma_f32_32x32x16_bf16 v[0:15], v[182:185], v[230:233], v[0:15]
	v_max3_f32 v242, v242, v78, v79
	v_mov_b32_e32 v243, v242
	v_mfma_f32_32x32x16_bf16 v[48:63], v[144:147], v[202:205], v[48:63]
	ds_read_b64_tr_b16 v[202:203], v160 offset:0x400
	ds_read_b64_tr_b16 v[204:205], v160 offset:0xc00
	v_permlane32_swap_b32_e32 v242, v243
	v_max_f32_e32 v242, v242, v243
	v_mfma_f32_32x32x16_bf16 v[48:63], v[136:139], v[210:213], v[48:63]
	ds_read_b64_tr_b16 v[210:211], v160 offset:0x1400
	ds_read_b64_tr_b16 v[212:213], v160 offset:0x1c00
	v_sub_f32_e32 v243, v242, v134
	v_max_f32_e32 v242, v134, v242
	v_sub_f32_e32 v148, v134, v242
	v_mul_f32_e32 v148, 0x3e0293ee, v148
	v_mfma_f32_32x32x16_bf16 v[48:63], v[140:143], v[214:217], v[48:63]
	ds_read_b64_tr_b16 v[214:215], v160 offset:0x2400
	ds_read_b64_tr_b16 v[216:217], v160 offset:0x2c00
	ds_read_b64_tr_b16 v[218:219], v160 offset:0x3400
	ds_read_b64_tr_b16 v[220:221], v160 offset:0x3c00
	v_exp_f32_e32 v148, v148
	v_cmp_ge_f32_e32 vcc, s15, v243
	s_cmp_eq_u64 vcc, exec
	s_cselect_b64 s[8:9], -1, 0
	s_waitcnt lgkmcnt(0)
	v_mfma_f32_32x32x16_bf16 v[48:63], v[182:185], v[222:225], v[48:63]
	v_cndmask_b32_e64 v177, v148, 1.0, s[8:9]
	v_cndmask_b32_e64 v175, v242, v134, s[8:9]
	v_mul_f32_e32 v244, 0xbe0293ee, v175
	v_fmamk_f32 v80, v80, 0x3e0293ee, v244
	v_fmamk_f32 v81, v81, 0x3e0293ee, v244
	v_fmamk_f32 v82, v82, 0x3e0293ee, v244
	v_fmamk_f32 v83, v83, 0x3e0293ee, v244
	v_mfma_f32_32x32x16_bf16 v[32:47], v[144:147], v[202:205], v[32:47]
	ds_read_b64_tr_b16 v[202:203], v160 offset:0x600
	ds_read_b64_tr_b16 v[204:205], v160 offset:0xe00
	v_fmamk_f32 v84, v84, 0x3e0293ee, v244
	v_fmamk_f32 v85, v85, 0x3e0293ee, v244
	v_fmamk_f32 v86, v86, 0x3e0293ee, v244
	v_fmamk_f32 v87, v87, 0x3e0293ee, v244
	v_fmamk_f32 v88, v88, 0x3e0293ee, v244
	v_fmamk_f32 v89, v89, 0x3e0293ee, v244
	v_fmamk_f32 v90, v90, 0x3e0293ee, v244
	v_fmamk_f32 v91, v91, 0x3e0293ee, v244
	v_mfma_f32_32x32x16_bf16 v[32:47], v[136:139], v[210:213], v[32:47]
	ds_read_b64_tr_b16 v[210:211], v160 offset:0x1600
	ds_read_b64_tr_b16 v[212:213], v160 offset:0x1e00
	v_fmamk_f32 v92, v92, 0x3e0293ee, v244
	v_fmamk_f32 v93, v93, 0x3e0293ee, v244
	v_fmamk_f32 v94, v94, 0x3e0293ee, v244
	v_fmamk_f32 v95, v95, 0x3e0293ee, v244
	v_fmamk_f32 v134, v72, 0x3e0293ee, v244
	v_fmamk_f32 v135, v73, 0x3e0293ee, v244
	v_fmamk_f32 v148, v74, 0x3e0293ee, v244
	v_fmamk_f32 v149, v75, 0x3e0293ee, v244
	v_mfma_f32_32x32x16_bf16 v[32:47], v[140:143], v[214:217], v[32:47]
	ds_read_b64_tr_b16 v[214:215], v160 offset:0x2600
	ds_read_b64_tr_b16 v[216:217], v160 offset:0x2e00
	ds_read_b64_tr_b16 v[222:223], v160 offset:0x3600
	ds_read_b64_tr_b16 v[224:225], v160 offset:0x3e00
	v_exp_f32_e32 v190, v80
	v_exp_f32_e32 v191, v81
	v_exp_f32_e32 v192, v82
	s_waitcnt lgkmcnt(0)
	v_mfma_f32_32x32x16_bf16 v[32:47], v[182:185], v[218:221], v[32:47]
	v_exp_f32_e32 v193, v83
	v_exp_f32_e32 v194, v84
	v_exp_f32_e32 v196, v85
	v_mfma_f32_32x32x16_bf16 v[16:31], v[144:147], v[202:205], v[16:31]
	v_fmamk_f32 v144, v78, 0x3e0293ee, v244
	v_fmamk_f32 v145, v79, 0x3e0293ee, v244
	v_fmamk_f32 v146, v76, 0x3e0293ee, v244
	v_fmamk_f32 v147, v77, 0x3e0293ee, v244
	v_exp_f32_e32 v195, v86
	v_exp_f32_e32 v197, v87
	v_mfma_f32_32x32x16_bf16 v[16:31], v[136:139], v[210:213], v[16:31]
	v_fmamk_f32 v136, v70, 0x3e0293ee, v244
	v_fmamk_f32 v137, v71, 0x3e0293ee, v244
	v_fmamk_f32 v138, v68, 0x3e0293ee, v244
	v_fmamk_f32 v139, v69, 0x3e0293ee, v244
	v_exp_f32_e32 v186, v91
	v_exp_f32_e32 v187, v93
	v_mfma_f32_32x32x16_bf16 v[16:31], v[140:143], v[214:217], v[16:31]
	v_fmamk_f32 v140, v66, 0x3e0293ee, v244
	v_fmamk_f32 v141, v67, 0x3e0293ee, v244
	v_fmamk_f32 v142, v64, 0x3e0293ee, v244
	v_fmamk_f32 v143, v65, 0x3e0293ee, v244
	v_exp_f32_e32 v188, v94
	v_exp_f32_e32 v189, v95
	v_mfma_f32_32x32x16_bf16 v[16:31], v[182:185], v[222:225], v[16:31]
	v_exp_f32_e32 v182, v88
	v_exp_f32_e32 v183, v89
	v_exp_f32_e32 v184, v90
	v_exp_f32_e32 v185, v92
	v_cmp_gt_f32_e32 vcc, 1.0, v177
	s_waitcnt vmcnt(0)
	s_barrier
	s_add_u32 m0, s86, 0x4000
	s_nop 0
	global_load_lds_dwordx4 v249, s[84:85]
	s_add_u32 m0, s86, 0x4380
	s_nop 0
	global_load_lds_dwordx4 v249, s[84:85] offset:128
	s_add_u32 s84, s84, 0x8000
	s_addc_u32 s85, s85, 0
	s_cbranch_vccz .LBB0_441
	s_and_saveexec_b64 s[2:3], s[6:7]
	ds_write_b32 v158, v177 offset:128
	s_or_b64 exec, exec, s[2:3]
	s_waitcnt lgkmcnt(0)
	v_add_u32_e32 v242, v131, v128
	ds_read_b128 v[226:229], v242 offset:224
	ds_read_b128 v[230:233], v242 offset:192
	ds_read_b128 v[234:237], v242 offset:160
	ds_read_b128 v[238:241], v242 offset:128
	s_waitcnt lgkmcnt(3)
	v_pk_mul_f32 v[12:13], v[12:13], v[226:227]
	s_waitcnt lgkmcnt(2)
	v_pk_mul_f32 v[8:9], v[8:9], v[230:231]
	s_waitcnt lgkmcnt(1)
	v_pk_mul_f32 v[4:5], v[4:5], v[234:235]
	v_pk_mul_f32 v[14:15], v[14:15], v[228:229]
	v_pk_mul_f32 v[10:11], v[10:11], v[232:233]
	v_pk_mul_f32 v[6:7], v[6:7], v[236:237]
	s_waitcnt lgkmcnt(0)
	v_pk_mul_f32 v[2:3], v[2:3], v[240:241]
	v_pk_mul_f32 v[0:1], v[0:1], v[238:239]
	v_pk_mul_f32 v[60:61], v[60:61], v[226:227]
	v_pk_mul_f32 v[56:57], v[56:57], v[230:231]
	v_pk_mul_f32 v[52:53], v[52:53], v[234:235]
	v_pk_mul_f32 v[62:63], v[62:63], v[228:229]
	v_pk_mul_f32 v[58:59], v[58:59], v[232:233]
	v_pk_mul_f32 v[54:55], v[54:55], v[236:237]
	v_pk_mul_f32 v[50:51], v[50:51], v[240:241]
	v_pk_mul_f32 v[48:49], v[48:49], v[238:239]
	v_pk_mul_f32 v[44:45], v[44:45], v[226:227]
	v_pk_mul_f32 v[40:41], v[40:41], v[230:231]
	v_pk_mul_f32 v[36:37], v[36:37], v[234:235]
	v_pk_mul_f32 v[46:47], v[46:47], v[228:229]
	v_pk_mul_f32 v[42:43], v[42:43], v[232:233]
	v_pk_mul_f32 v[38:39], v[38:39], v[236:237]
	v_pk_mul_f32 v[34:35], v[34:35], v[240:241]
	v_pk_mul_f32 v[32:33], v[32:33], v[238:239]
	v_pk_mul_f32 v[28:29], v[28:29], v[226:227]
	v_pk_mul_f32 v[24:25], v[24:25], v[230:231]
	v_pk_mul_f32 v[20:21], v[20:21], v[234:235]
	v_pk_mul_f32 v[30:31], v[30:31], v[228:229]
	v_pk_mul_f32 v[26:27], v[26:27], v[232:233]
	v_pk_mul_f32 v[22:23], v[22:23], v[236:237]
	v_pk_mul_f32 v[18:19], v[18:19], v[240:241]
	v_pk_mul_f32 v[16:17], v[16:17], v[238:239]
